# single-hop barrier release: in grid barriers 1-3 the non-leader workgroups poll the top-level generation word instead of their XCD's word
# speedup vs baseline: 1.0044x; 1.0044x over previous
; DI unsigned xb_ld(unsigned* p)              { return __hip_atomic_load(p, __ATOMIC_RELAXED, __HIP_MEMORY_SCOPE_AGENT); }
; DI unsigned xb_add(unsigned* p, unsigned v) { return __hip_atomic_fetch_add(p, v, __ATOMIC_RELAXED, __HIP_MEMORY_SCOPE_AGENT); }
; #define XB_SPIN(cond, bar) do { unsigned _sp = 0; while (cond) { __builtin_amdgcn_s_sleep(1); \
;     if ((++_sp & 255u) == 0u) { if (xb_ld(&(bar)[XB_TMO])) break; if (_sp > XB_SPIN_CAP) { atomicAdd(&(bar)[XB_TMO], 1u); break; } } } } while (0)
; DI void xcd_barrier(const XcdBarrier& b) {
;     ...
;         const unsigned old = xb_add(&bar[XB_XSUB(b.x)], 1u);
;         const unsigned gen = old / nloc;
;         if (old + 1u == (gen + 1u) * nloc) {
;             __builtin_amdgcn_fence(__ATOMIC_RELEASE, "agent");
;             asm volatile("s_waitcnt vmcnt(0)" ::: "memory");
;             const unsigned og = xb_add(&bar[XB_TOP], 1u);
;             const unsigned tg = og / nx;
;             if (og + 1u == (tg + 1u) * nx) xb_add(&bar[XB_TOPGEN], 1u);
;             else XB_SPIN(xb_ld(&bar[XB_TOPGEN]) == tg, bar);
;             __builtin_amdgcn_fence(__ATOMIC_ACQUIRE, "agent");
;             xb_add(&bar[XB_XGEN(b.x)], 1u);
;             asm volatile("s_waitcnt vmcnt(0)" ::: "memory");
;         } else {
;             XB_SPIN(xb_ld(&bar[XB_XGEN(b.x)]) == gen, bar);
.LBB0_104:
	s_or_b64 exec, exec, s[10:11]
	v_cvt_f32_u32_e32 v4, v2
	s_waitcnt vmcnt(0)
	v_readfirstlane_b32 s8, v3
	v_sub_u32_e32 v3, 0, v2
	v_rcp_iflag_f32_e32 v4, v4
	v_add_u32_e32 v5, s8, v1
	v_mul_f32_e32 v4, 0x4f7ffffe, v4
	v_cvt_u32_f32_e32 v4, v4
	v_mul_lo_u32 v1, v3, v4
	v_mul_hi_u32 v1, v4, v1
	v_add_u32_e32 v1, v4, v1
	v_mul_hi_u32 v1, v5, v1
	v_mul_lo_u32 v3, v1, v2
	v_sub_u32_e32 v3, v5, v3
	v_add_u32_e32 v4, 1, v1
	v_cmp_ge_u32_e32 vcc, v3, v2
	s_nop 1
	v_cndmask_b32_e32 v1, v1, v4, vcc
	v_sub_u32_e32 v4, v3, v2
	v_cndmask_b32_e32 v3, v3, v4, vcc
	v_add_u32_e32 v4, 1, v1
	v_cmp_ge_u32_e32 vcc, v3, v2
	v_add_u32_e32 v3, 1, v5
	s_nop 0
	v_cndmask_b32_e32 v1, v1, v4, vcc
	v_mul_lo_u32 v4, v2, v1
	v_add_u32_e32 v2, v4, v2
	v_cmp_ne_u32_e32 vcc, v3, v2
	s_and_saveexec_b64 s[8:9], vcc
	s_xor_b64 s[8:9], exec, s[8:9]
	s_cbranch_execz .LBB0_118
	s_waitcnt lgkmcnt(0)
	buffer_inv sc1
	v_mov_b32_e32 v0, 0x3100
	global_load_dword v0, v0, s[46:47] offset:1024 sc1
	s_add_u32 s14, s46, 0x3500
	s_addc_u32 s15, s47, 0
	s_waitcnt vmcnt(0)
	v_cmp_eq_u32_e32 vcc, v0, v1
	s_and_saveexec_b64 s[10:11], vcc
	s_cbranch_execz .LBB0_117
	s_add_u32 s12, s44, 0xf690200
	s_addc_u32 s13, s45, 0
	s_mov_b32 s26, 1
	s_mov_b64 s[16:17], 0
	v_mov_b32_e32 v0, 0
	s_branch .LBB0_108
